# weight transposes: issue all 32 row loads (+32 gain loads) per block before one wait instead of a vmcnt(0) after every 4-byte load
# speedup vs baseline: 1.0490x; 1.0163x over previous
.LBB0_10:
	v_mul_hi_i32 v2, v30, s3
	v_add_u32_e32 v2, v2, v30
	v_lshrrev_b32_e32 v3, 31, v2
	v_ashrrev_i32_e32 v2, 7, v2
	v_add_u32_e32 v2, v2, v3
	v_mul_lo_u32 v3, v2, s4
	v_sub_u32_e32 v3, v30, v3
	v_lshlrev_b32_e32 v43, 5, v3
	v_lshlrev_b32_e32 v10, 6, v2
	v_or_b32_e32 v2, v43, v7
	v_ashrrev_i32_e32 v3, 31, v2
	v_lshlrev_b64 v[26:27], 2, v[2:3]
	v_or_b32_e32 v11, v38, v10
	v_mad_i64_i32 v[12:13], s[18:19], v11, s24, v[26:27]
	v_or_b32_e32 v11, v39, v10
	v_mad_i64_i32 v[14:15], s[18:19], v11, s24, v[26:27]
	v_or_b32_e32 v11, v40, v10
	v_mad_i64_i32 v[16:17], s[18:19], v11, s24, v[26:27]
	v_or_b32_e32 v11, v41, v10
	v_or_b32_e32 v4, v36, v10
	v_mad_i64_i32 v[22:23], s[18:19], v11, s24, v[26:27]
	v_or_b32_e32 v11, v42, v10
	v_cmp_gt_i32_e32 vcc, s5, v2
	v_mad_i64_i32 v[2:3], s[18:19], v4, s24, v[26:27]
	v_or_b32_e32 v4, v37, v10
	v_mad_i64_i32 v[24:25], s[18:19], v11, s24, v[26:27]
	v_or_b32_e32 v11, v6, v10
	v_mad_i64_i32 v[4:5], s[18:19], v4, s24, v[26:27]
	v_mad_i64_i32 v[26:27], s[18:19], v11, s24, v[26:27]
	v_lshl_add_u64 v[2:3], s[8:9], 0, v[2:3]
	v_lshl_add_u64 v[4:5], s[8:9], 0, v[4:5]
	v_lshl_add_u64 v[12:13], s[8:9], 0, v[12:13]
	v_lshl_add_u64 v[14:15], s[8:9], 0, v[14:15]
	v_lshl_add_u64 v[16:17], s[8:9], 0, v[16:17]
	v_lshl_add_u64 v[22:23], s[8:9], 0, v[22:23]
	v_lshl_add_u64 v[24:25], s[8:9], 0, v[24:25]
	v_lshl_add_u64 v[26:27], s[8:9], 0, v[26:27]
	v_mov_b32_e32 v11, v35
	v_mov_b32_e32 v80, 0
	v_mov_b32_e32 v81, 0
	v_mov_b32_e32 v82, 0
	v_mov_b32_e32 v83, 0
	v_mov_b32_e32 v84, 0
	v_mov_b32_e32 v85, 0
	v_mov_b32_e32 v86, 0
	v_mov_b32_e32 v87, 0
	v_mov_b32_e32 v88, 0
	v_mov_b32_e32 v89, 0
	v_mov_b32_e32 v90, 0
	v_mov_b32_e32 v91, 0
	v_mov_b32_e32 v92, 0
	v_mov_b32_e32 v93, 0
	v_mov_b32_e32 v94, 0
	v_mov_b32_e32 v95, 0
	v_mov_b32_e32 v96, 0
	v_mov_b32_e32 v97, 0
	v_mov_b32_e32 v98, 0
	v_mov_b32_e32 v99, 0
	v_mov_b32_e32 v100, 0
	v_mov_b32_e32 v101, 0
	v_mov_b32_e32 v102, 0
	v_mov_b32_e32 v103, 0
	v_mov_b32_e32 v104, 0
	v_mov_b32_e32 v105, 0
	v_mov_b32_e32 v106, 0
	v_mov_b32_e32 v107, 0
	v_mov_b32_e32 v108, 0
	v_mov_b32_e32 v109, 0
	v_mov_b32_e32 v110, 0
	v_mov_b32_e32 v111, 0
	s_and_saveexec_b64 s[20:21], vcc
	global_load_dword v80, v[26:27], off
	global_load_dword v81, v[24:25], off
	global_load_dword v82, v[22:23], off
	global_load_dword v83, v[16:17], off
	global_load_dword v84, v[14:15], off
	global_load_dword v85, v[12:13], off
	global_load_dword v86, v[4:5], off
	global_load_dword v87, v[2:3], off
	s_mov_b64 s[18:19], 0x5c400
	v_lshl_add_u64 v[144:145], v[26:27], 0, s[18:19]
	global_load_dword v88, v[144:145], off
	v_lshl_add_u64 v[144:145], v[24:25], 0, s[18:19]
	global_load_dword v89, v[144:145], off
	v_lshl_add_u64 v[144:145], v[22:23], 0, s[18:19]
	global_load_dword v90, v[144:145], off
	v_lshl_add_u64 v[144:145], v[16:17], 0, s[18:19]
	global_load_dword v91, v[144:145], off
	v_lshl_add_u64 v[144:145], v[14:15], 0, s[18:19]
	global_load_dword v92, v[144:145], off
	v_lshl_add_u64 v[144:145], v[12:13], 0, s[18:19]
	global_load_dword v93, v[144:145], off
	v_lshl_add_u64 v[144:145], v[4:5], 0, s[18:19]
	global_load_dword v94, v[144:145], off
	v_lshl_add_u64 v[144:145], v[2:3], 0, s[18:19]
	global_load_dword v95, v[144:145], off
	s_mov_b64 s[18:19], 0xb8800
	v_lshl_add_u64 v[144:145], v[26:27], 0, s[18:19]
	global_load_dword v96, v[144:145], off
	v_lshl_add_u64 v[144:145], v[24:25], 0, s[18:19]
	global_load_dword v97, v[144:145], off
	v_lshl_add_u64 v[144:145], v[22:23], 0, s[18:19]
	global_load_dword v98, v[144:145], off
	v_lshl_add_u64 v[144:145], v[16:17], 0, s[18:19]
	global_load_dword v99, v[144:145], off
	v_lshl_add_u64 v[144:145], v[14:15], 0, s[18:19]
	global_load_dword v100, v[144:145], off
	v_lshl_add_u64 v[144:145], v[12:13], 0, s[18:19]
	global_load_dword v101, v[144:145], off
	v_lshl_add_u64 v[144:145], v[4:5], 0, s[18:19]
	global_load_dword v102, v[144:145], off
	v_lshl_add_u64 v[144:145], v[2:3], 0, s[18:19]
	global_load_dword v103, v[144:145], off
	s_mov_b64 s[18:19], 0x114c00
	v_lshl_add_u64 v[144:145], v[26:27], 0, s[18:19]
	global_load_dword v104, v[144:145], off
	v_lshl_add_u64 v[144:145], v[24:25], 0, s[18:19]
	global_load_dword v105, v[144:145], off
	v_lshl_add_u64 v[144:145], v[22:23], 0, s[18:19]
	global_load_dword v106, v[144:145], off
	v_lshl_add_u64 v[144:145], v[16:17], 0, s[18:19]
	global_load_dword v107, v[144:145], off
	v_lshl_add_u64 v[144:145], v[14:15], 0, s[18:19]
	global_load_dword v108, v[144:145], off
	v_lshl_add_u64 v[144:145], v[12:13], 0, s[18:19]
	global_load_dword v109, v[144:145], off
	v_lshl_add_u64 v[144:145], v[4:5], 0, s[18:19]
	global_load_dword v110, v[144:145], off
	v_lshl_add_u64 v[144:145], v[2:3], 0, s[18:19]
	global_load_dword v111, v[144:145], off
	s_or_b64 exec, exec, s[20:21]
	s_waitcnt vmcnt(24)
	ds_write_b32 v11, v80 offset:0
	ds_write_b32 v11, v81 offset:264
	ds_write_b32 v11, v82 offset:528
	ds_write_b32 v11, v83 offset:792
	ds_write_b32 v11, v84 offset:1056
	ds_write_b32 v11, v85 offset:1320
	ds_write_b32 v11, v86 offset:1584
	ds_write_b32 v11, v87 offset:1848
	s_waitcnt vmcnt(16)
	ds_write_b32 v11, v88 offset:2112
	ds_write_b32 v11, v89 offset:2376
	ds_write_b32 v11, v90 offset:2640
	ds_write_b32 v11, v91 offset:2904
	ds_write_b32 v11, v92 offset:3168
	ds_write_b32 v11, v93 offset:3432
	ds_write_b32 v11, v94 offset:3696
	ds_write_b32 v11, v95 offset:3960
	s_waitcnt vmcnt(8)
	ds_write_b32 v11, v96 offset:4224
	ds_write_b32 v11, v97 offset:4488
	ds_write_b32 v11, v98 offset:4752
	ds_write_b32 v11, v99 offset:5016
	ds_write_b32 v11, v100 offset:5280
	ds_write_b32 v11, v101 offset:5544
	ds_write_b32 v11, v102 offset:5808
	ds_write_b32 v11, v103 offset:6072
	s_waitcnt vmcnt(0)
	ds_write_b32 v11, v104 offset:6336
	ds_write_b32 v11, v105 offset:6600
	ds_write_b32 v11, v106 offset:6864
	ds_write_b32 v11, v107 offset:7128
	ds_write_b32 v11, v108 offset:7392
	ds_write_b32 v11, v109 offset:7656
	ds_write_b32 v11, v110 offset:7920
	ds_write_b32 v11, v111 offset:8184

.LBB0_61:
	v_ashrrev_i32_e32 v2, 31, v16
	v_lshrrev_b32_e32 v2, 27, v2
	v_add_u32_e32 v2, v16, v2
	v_and_b32_e32 v3, 0x7ffffe0, v2
	v_sub_u32_e32 v3, v16, v3
	v_lshlrev_b32_e32 v2, 1, v2
	v_and_b32_e32 v10, 0xffffffc0, v2
	v_lshlrev_b32_e32 v26, 5, v3
	v_or_b32_e32 v2, v26, v7
	v_ashrrev_i32_e32 v11, 31, v10
	v_ashrrev_i32_e32 v3, 31, v2
	v_or_b32_e32 v4, v6, v10
	v_mov_b32_e32 v5, v11
	v_cmp_gt_i32_e64 s[8:9], s5, v2
	v_lshl_add_u64 v[2:3], v[2:3], 2, s[20:21]
	v_lshl_add_u64 v[12:13], v[4:5], 2, s[24:25]
	v_mov_b32_e32 v5, v25
	v_mov_b32_e32 v144, v4
	v_mov_b32_e32 v145, 0
	v_lshlrev_b64 v[144:145], 12, v[144:145]
	v_lshl_add_u64 v[144:145], v[2:3], 0, v[144:145]
	s_mov_b64 s[100:101], 0x2000
	v_mov_b32_e32 v80, 0
	v_mov_b32_e32 v81, 0
	v_mov_b32_e32 v82, 0
	v_mov_b32_e32 v83, 0
	v_mov_b32_e32 v84, 0
	v_mov_b32_e32 v85, 0
	v_mov_b32_e32 v86, 0
	v_mov_b32_e32 v87, 0
	v_mov_b32_e32 v88, 0
	v_mov_b32_e32 v89, 0
	v_mov_b32_e32 v90, 0
	v_mov_b32_e32 v91, 0
	v_mov_b32_e32 v92, 0
	v_mov_b32_e32 v93, 0
	v_mov_b32_e32 v94, 0
	v_mov_b32_e32 v95, 0
	v_mov_b32_e32 v96, 0
	v_mov_b32_e32 v97, 0
	v_mov_b32_e32 v98, 0
	v_mov_b32_e32 v99, 0
	v_mov_b32_e32 v100, 0
	v_mov_b32_e32 v101, 0
	v_mov_b32_e32 v102, 0
	v_mov_b32_e32 v103, 0
	v_mov_b32_e32 v104, 0
	v_mov_b32_e32 v105, 0
	v_mov_b32_e32 v106, 0
	v_mov_b32_e32 v107, 0
	v_mov_b32_e32 v108, 0
	v_mov_b32_e32 v109, 0
	v_mov_b32_e32 v110, 0
	v_mov_b32_e32 v111, 0
	s_and_saveexec_b64 s[26:27], s[8:9]
	global_load_dword v80, v[144:145], off
	v_lshl_add_u64 v[144:145], v[144:145], 0, s[100:101]
	global_load_dword v81, v[144:145], off
	v_lshl_add_u64 v[144:145], v[144:145], 0, s[100:101]
	global_load_dword v82, v[144:145], off
	v_lshl_add_u64 v[144:145], v[144:145], 0, s[100:101]
	global_load_dword v83, v[144:145], off
	v_lshl_add_u64 v[144:145], v[144:145], 0, s[100:101]
	global_load_dword v84, v[144:145], off
	v_lshl_add_u64 v[144:145], v[144:145], 0, s[100:101]
	global_load_dword v85, v[144:145], off
	v_lshl_add_u64 v[144:145], v[144:145], 0, s[100:101]
	global_load_dword v86, v[144:145], off
	v_lshl_add_u64 v[144:145], v[144:145], 0, s[100:101]
	global_load_dword v87, v[144:145], off
	v_lshl_add_u64 v[144:145], v[144:145], 0, s[100:101]
	global_load_dword v88, v[144:145], off
	v_lshl_add_u64 v[144:145], v[144:145], 0, s[100:101]
	global_load_dword v89, v[144:145], off
	v_lshl_add_u64 v[144:145], v[144:145], 0, s[100:101]
	global_load_dword v90, v[144:145], off
	v_lshl_add_u64 v[144:145], v[144:145], 0, s[100:101]
	global_load_dword v91, v[144:145], off
	v_lshl_add_u64 v[144:145], v[144:145], 0, s[100:101]
	global_load_dword v92, v[144:145], off
	v_lshl_add_u64 v[144:145], v[144:145], 0, s[100:101]
	global_load_dword v93, v[144:145], off
	v_lshl_add_u64 v[144:145], v[144:145], 0, s[100:101]
	global_load_dword v94, v[144:145], off
	v_lshl_add_u64 v[144:145], v[144:145], 0, s[100:101]
	global_load_dword v95, v[144:145], off
	v_lshl_add_u64 v[144:145], v[144:145], 0, s[100:101]
	global_load_dword v96, v[144:145], off
	v_lshl_add_u64 v[144:145], v[144:145], 0, s[100:101]
	global_load_dword v97, v[144:145], off
	v_lshl_add_u64 v[144:145], v[144:145], 0, s[100:101]
	global_load_dword v98, v[144:145], off
	v_lshl_add_u64 v[144:145], v[144:145], 0, s[100:101]
	global_load_dword v99, v[144:145], off
	v_lshl_add_u64 v[144:145], v[144:145], 0, s[100:101]
	global_load_dword v100, v[144:145], off
	v_lshl_add_u64 v[144:145], v[144:145], 0, s[100:101]
	global_load_dword v101, v[144:145], off
	v_lshl_add_u64 v[144:145], v[144:145], 0, s[100:101]
	global_load_dword v102, v[144:145], off
	v_lshl_add_u64 v[144:145], v[144:145], 0, s[100:101]
	global_load_dword v103, v[144:145], off
	v_lshl_add_u64 v[144:145], v[144:145], 0, s[100:101]
	global_load_dword v104, v[144:145], off
	v_lshl_add_u64 v[144:145], v[144:145], 0, s[100:101]
	global_load_dword v105, v[144:145], off
	v_lshl_add_u64 v[144:145], v[144:145], 0, s[100:101]
	global_load_dword v106, v[144:145], off
	v_lshl_add_u64 v[144:145], v[144:145], 0, s[100:101]
	global_load_dword v107, v[144:145], off
	v_lshl_add_u64 v[144:145], v[144:145], 0, s[100:101]
	global_load_dword v108, v[144:145], off
	v_lshl_add_u64 v[144:145], v[144:145], 0, s[100:101]
	global_load_dword v109, v[144:145], off
	v_lshl_add_u64 v[144:145], v[144:145], 0, s[100:101]
	global_load_dword v110, v[144:145], off
	v_lshl_add_u64 v[144:145], v[144:145], 0, s[100:101]
	global_load_dword v111, v[144:145], off
	s_or_b64 exec, exec, s[26:27]
	s_and_b64 vcc, exec, s[6:7]
	s_cbranch_vccnz .Ltr_nogain_1
	v_cmp_gt_i32_e32 vcc, s5, v4
	s_and_saveexec_b64 s[26:27], vcc
	v_mov_b32_e32 v146, v4
	v_mov_b32_e32 v147, 0
	v_lshl_add_u64 v[146:147], v[146:147], 2, s[18:19]
	global_load_dword v112, v[146:147], off offset:0
	global_load_dword v113, v[146:147], off offset:8
	global_load_dword v114, v[146:147], off offset:16
	global_load_dword v115, v[146:147], off offset:24
	global_load_dword v116, v[146:147], off offset:32
	global_load_dword v117, v[146:147], off offset:40
	global_load_dword v118, v[146:147], off offset:48
	global_load_dword v119, v[146:147], off offset:56
	global_load_dword v120, v[146:147], off offset:64
	global_load_dword v121, v[146:147], off offset:72
	global_load_dword v122, v[146:147], off offset:80
	global_load_dword v123, v[146:147], off offset:88
	global_load_dword v124, v[146:147], off offset:96
	global_load_dword v125, v[146:147], off offset:104
	global_load_dword v126, v[146:147], off offset:112
	global_load_dword v127, v[146:147], off offset:120
	global_load_dword v128, v[146:147], off offset:128
	global_load_dword v129, v[146:147], off offset:136
	global_load_dword v130, v[146:147], off offset:144
	global_load_dword v131, v[146:147], off offset:152
	global_load_dword v132, v[146:147], off offset:160
	global_load_dword v133, v[146:147], off offset:168
	global_load_dword v134, v[146:147], off offset:176
	global_load_dword v135, v[146:147], off offset:184
	global_load_dword v136, v[146:147], off offset:192
	global_load_dword v137, v[146:147], off offset:200
	global_load_dword v138, v[146:147], off offset:208
	global_load_dword v139, v[146:147], off offset:216
	global_load_dword v140, v[146:147], off offset:224
	global_load_dword v141, v[146:147], off offset:232
	global_load_dword v142, v[146:147], off offset:240
	global_load_dword v143, v[146:147], off offset:248
	s_waitcnt vmcnt(0)
	v_mul_f32_e32 v80, v80, v112
	v_mul_f32_e32 v81, v81, v113
	v_mul_f32_e32 v82, v82, v114
	v_mul_f32_e32 v83, v83, v115
	v_mul_f32_e32 v84, v84, v116
	v_mul_f32_e32 v85, v85, v117
	v_mul_f32_e32 v86, v86, v118
	v_mul_f32_e32 v87, v87, v119
	v_mul_f32_e32 v88, v88, v120
	v_mul_f32_e32 v89, v89, v121
	v_mul_f32_e32 v90, v90, v122
	v_mul_f32_e32 v91, v91, v123
	v_mul_f32_e32 v92, v92, v124
	v_mul_f32_e32 v93, v93, v125
	v_mul_f32_e32 v94, v94, v126
	v_mul_f32_e32 v95, v95, v127
	v_mul_f32_e32 v96, v96, v128
	v_mul_f32_e32 v97, v97, v129
	v_mul_f32_e32 v98, v98, v130
	v_mul_f32_e32 v99, v99, v131
	v_mul_f32_e32 v100, v100, v132
	v_mul_f32_e32 v101, v101, v133
	v_mul_f32_e32 v102, v102, v134
	v_mul_f32_e32 v103, v103, v135
	v_mul_f32_e32 v104, v104, v136
	v_mul_f32_e32 v105, v105, v137
	v_mul_f32_e32 v106, v106, v138
	v_mul_f32_e32 v107, v107, v139
	v_mul_f32_e32 v108, v108, v140
	v_mul_f32_e32 v109, v109, v141
	v_mul_f32_e32 v110, v110, v142
	v_mul_f32_e32 v111, v111, v143
	s_or_b64 exec, exec, s[26:27]
.Ltr_nogain_1:
	s_waitcnt vmcnt(24)
	ds_write_b32 v5, v80 offset:0
	ds_write_b32 v5, v81 offset:264
	ds_write_b32 v5, v82 offset:528
	ds_write_b32 v5, v83 offset:792
	ds_write_b32 v5, v84 offset:1056
	ds_write_b32 v5, v85 offset:1320
	ds_write_b32 v5, v86 offset:1584
	ds_write_b32 v5, v87 offset:1848
	s_waitcnt vmcnt(16)
	ds_write_b32 v5, v88 offset:2112
	ds_write_b32 v5, v89 offset:2376
	ds_write_b32 v5, v90 offset:2640
	ds_write_b32 v5, v91 offset:2904
	ds_write_b32 v5, v92 offset:3168
	ds_write_b32 v5, v93 offset:3432
	ds_write_b32 v5, v94 offset:3696
	ds_write_b32 v5, v95 offset:3960
	s_waitcnt vmcnt(8)
	ds_write_b32 v5, v96 offset:4224
	ds_write_b32 v5, v97 offset:4488
	ds_write_b32 v5, v98 offset:4752
	ds_write_b32 v5, v99 offset:5016
	ds_write_b32 v5, v100 offset:5280
	ds_write_b32 v5, v101 offset:5544
	ds_write_b32 v5, v102 offset:5808
	ds_write_b32 v5, v103 offset:6072
	s_waitcnt vmcnt(0)
	ds_write_b32 v5, v104 offset:6336
	ds_write_b32 v5, v105 offset:6600
	ds_write_b32 v5, v106 offset:6864
	ds_write_b32 v5, v107 offset:7128
	ds_write_b32 v5, v108 offset:7392
	ds_write_b32 v5, v109 offset:7656
	ds_write_b32 v5, v110 offset:7920
	ds_write_b32 v5, v111 offset:8184

.LBB0_122:
	v_ashrrev_i32_e32 v2, 31, v14
	v_lshrrev_b32_e32 v2, 27, v2
	v_add_u32_e32 v2, v14, v2
	v_and_b32_e32 v3, 0x7ffffe0, v2
	v_sub_u32_e32 v3, v14, v3
	v_lshlrev_b32_e32 v2, 1, v2
	v_lshlrev_b32_e32 v24, 5, v3
	v_and_b32_e32 v10, 0xffffffc0, v2
	v_or_b32_e32 v2, v24, v7
	v_ashrrev_i32_e32 v3, 31, v2
	v_cmp_gt_i32_e32 vcc, s5, v2
	v_lshl_add_u64 v[2:3], v[2:3], 2, s[8:9]
	v_or_b32_e32 v4, v6, v10
	v_mov_b32_e32 v5, v23
	v_mov_b32_e32 v144, v4
	v_mov_b32_e32 v145, 0
	v_lshlrev_b64 v[144:145], 12, v[144:145]
	v_lshl_add_u64 v[144:145], v[2:3], 0, v[144:145]
	s_mov_b64 s[100:101], 0x2000
	v_mov_b32_e32 v80, 0
	v_mov_b32_e32 v81, 0
	v_mov_b32_e32 v82, 0
	v_mov_b32_e32 v83, 0
	v_mov_b32_e32 v84, 0
	v_mov_b32_e32 v85, 0
	v_mov_b32_e32 v86, 0
	v_mov_b32_e32 v87, 0
	v_mov_b32_e32 v88, 0
	v_mov_b32_e32 v89, 0
	v_mov_b32_e32 v90, 0
	v_mov_b32_e32 v91, 0
	v_mov_b32_e32 v92, 0
	v_mov_b32_e32 v93, 0
	v_mov_b32_e32 v94, 0
	v_mov_b32_e32 v95, 0
	v_mov_b32_e32 v96, 0
	v_mov_b32_e32 v97, 0
	v_mov_b32_e32 v98, 0
	v_mov_b32_e32 v99, 0
	v_mov_b32_e32 v100, 0
	v_mov_b32_e32 v101, 0
	v_mov_b32_e32 v102, 0
	v_mov_b32_e32 v103, 0
	v_mov_b32_e32 v104, 0
	v_mov_b32_e32 v105, 0
	v_mov_b32_e32 v106, 0
	v_mov_b32_e32 v107, 0
	v_mov_b32_e32 v108, 0
	v_mov_b32_e32 v109, 0
	v_mov_b32_e32 v110, 0
	v_mov_b32_e32 v111, 0
	s_and_saveexec_b64 s[18:19], vcc
	global_load_dword v80, v[144:145], off
	v_lshl_add_u64 v[144:145], v[144:145], 0, s[100:101]
	global_load_dword v81, v[144:145], off
	v_lshl_add_u64 v[144:145], v[144:145], 0, s[100:101]
	global_load_dword v82, v[144:145], off
	v_lshl_add_u64 v[144:145], v[144:145], 0, s[100:101]
	global_load_dword v83, v[144:145], off
	v_lshl_add_u64 v[144:145], v[144:145], 0, s[100:101]
	global_load_dword v84, v[144:145], off
	v_lshl_add_u64 v[144:145], v[144:145], 0, s[100:101]
	global_load_dword v85, v[144:145], off
	v_lshl_add_u64 v[144:145], v[144:145], 0, s[100:101]
	global_load_dword v86, v[144:145], off
	v_lshl_add_u64 v[144:145], v[144:145], 0, s[100:101]
	global_load_dword v87, v[144:145], off
	v_lshl_add_u64 v[144:145], v[144:145], 0, s[100:101]
	global_load_dword v88, v[144:145], off
	v_lshl_add_u64 v[144:145], v[144:145], 0, s[100:101]
	global_load_dword v89, v[144:145], off
	v_lshl_add_u64 v[144:145], v[144:145], 0, s[100:101]
	global_load_dword v90, v[144:145], off
	v_lshl_add_u64 v[144:145], v[144:145], 0, s[100:101]
	global_load_dword v91, v[144:145], off
	v_lshl_add_u64 v[144:145], v[144:145], 0, s[100:101]
	global_load_dword v92, v[144:145], off
	v_lshl_add_u64 v[144:145], v[144:145], 0, s[100:101]
	global_load_dword v93, v[144:145], off
	v_lshl_add_u64 v[144:145], v[144:145], 0, s[100:101]
	global_load_dword v94, v[144:145], off
	v_lshl_add_u64 v[144:145], v[144:145], 0, s[100:101]
	global_load_dword v95, v[144:145], off
	v_lshl_add_u64 v[144:145], v[144:145], 0, s[100:101]
	global_load_dword v96, v[144:145], off
	v_lshl_add_u64 v[144:145], v[144:145], 0, s[100:101]
	global_load_dword v97, v[144:145], off
	v_lshl_add_u64 v[144:145], v[144:145], 0, s[100:101]
	global_load_dword v98, v[144:145], off
	v_lshl_add_u64 v[144:145], v[144:145], 0, s[100:101]
	global_load_dword v99, v[144:145], off
	v_lshl_add_u64 v[144:145], v[144:145], 0, s[100:101]
	global_load_dword v100, v[144:145], off
	v_lshl_add_u64 v[144:145], v[144:145], 0, s[100:101]
	global_load_dword v101, v[144:145], off
	v_lshl_add_u64 v[144:145], v[144:145], 0, s[100:101]
	global_load_dword v102, v[144:145], off
	v_lshl_add_u64 v[144:145], v[144:145], 0, s[100:101]
	global_load_dword v103, v[144:145], off
	v_lshl_add_u64 v[144:145], v[144:145], 0, s[100:101]
	global_load_dword v104, v[144:145], off
	v_lshl_add_u64 v[144:145], v[144:145], 0, s[100:101]
	global_load_dword v105, v[144:145], off
	v_lshl_add_u64 v[144:145], v[144:145], 0, s[100:101]
	global_load_dword v106, v[144:145], off
	v_lshl_add_u64 v[144:145], v[144:145], 0, s[100:101]
	global_load_dword v107, v[144:145], off
	v_lshl_add_u64 v[144:145], v[144:145], 0, s[100:101]
	global_load_dword v108, v[144:145], off
	v_lshl_add_u64 v[144:145], v[144:145], 0, s[100:101]
	global_load_dword v109, v[144:145], off
	v_lshl_add_u64 v[144:145], v[144:145], 0, s[100:101]
	global_load_dword v110, v[144:145], off
	v_lshl_add_u64 v[144:145], v[144:145], 0, s[100:101]
	global_load_dword v111, v[144:145], off
	s_or_b64 exec, exec, s[18:19]
	s_waitcnt vmcnt(24)
	ds_write_b32 v5, v80 offset:0
	ds_write_b32 v5, v81 offset:264
	ds_write_b32 v5, v82 offset:528
	ds_write_b32 v5, v83 offset:792
	ds_write_b32 v5, v84 offset:1056
	ds_write_b32 v5, v85 offset:1320
	ds_write_b32 v5, v86 offset:1584
	ds_write_b32 v5, v87 offset:1848
	s_waitcnt vmcnt(16)
	ds_write_b32 v5, v88 offset:2112
	ds_write_b32 v5, v89 offset:2376
	ds_write_b32 v5, v90 offset:2640
	ds_write_b32 v5, v91 offset:2904
	ds_write_b32 v5, v92 offset:3168
	ds_write_b32 v5, v93 offset:3432
	ds_write_b32 v5, v94 offset:3696
	ds_write_b32 v5, v95 offset:3960
	s_waitcnt vmcnt(8)
	ds_write_b32 v5, v96 offset:4224
	ds_write_b32 v5, v97 offset:4488
	ds_write_b32 v5, v98 offset:4752
	ds_write_b32 v5, v99 offset:5016
	ds_write_b32 v5, v100 offset:5280
	ds_write_b32 v5, v101 offset:5544
	ds_write_b32 v5, v102 offset:5808
	ds_write_b32 v5, v103 offset:6072
	s_waitcnt vmcnt(0)
	ds_write_b32 v5, v104 offset:6336
	ds_write_b32 v5, v105 offset:6600
	ds_write_b32 v5, v106 offset:6864
	ds_write_b32 v5, v107 offset:7128
	ds_write_b32 v5, v108 offset:7392
	ds_write_b32 v5, v109 offset:7656
	ds_write_b32 v5, v110 offset:7920
	ds_write_b32 v5, v111 offset:8184

.LBB0_180:
	v_ashrrev_i32_e32 v2, 31, v14
	v_lshrrev_b32_e32 v2, 27, v2
	v_add_u32_e32 v2, v14, v2
	v_and_b32_e32 v3, 0x7ffffe0, v2
	v_sub_u32_e32 v3, v14, v3
	v_lshlrev_b32_e32 v2, 1, v2
	v_lshlrev_b32_e32 v24, 5, v3
	v_and_b32_e32 v10, 0xffffffc0, v2
	v_or_b32_e32 v2, v24, v7
	v_ashrrev_i32_e32 v3, 31, v2
	v_cmp_gt_i32_e32 vcc, s3, v2
	v_lshl_add_u64 v[2:3], v[2:3], 2, s[8:9]
	v_or_b32_e32 v4, v6, v10
	v_mov_b32_e32 v5, v23
	v_mov_b32_e32 v144, v4
	v_mov_b32_e32 v145, 0
	v_lshlrev_b64 v[144:145], 12, v[144:145]
	v_lshl_add_u64 v[144:145], v[2:3], 0, v[144:145]
	s_mov_b64 s[100:101], 0x2000
	v_mov_b32_e32 v80, 0
	v_mov_b32_e32 v81, 0
	v_mov_b32_e32 v82, 0
	v_mov_b32_e32 v83, 0
	v_mov_b32_e32 v84, 0
	v_mov_b32_e32 v85, 0
	v_mov_b32_e32 v86, 0
	v_mov_b32_e32 v87, 0
	v_mov_b32_e32 v88, 0
	v_mov_b32_e32 v89, 0
	v_mov_b32_e32 v90, 0
	v_mov_b32_e32 v91, 0
	v_mov_b32_e32 v92, 0
	v_mov_b32_e32 v93, 0
	v_mov_b32_e32 v94, 0
	v_mov_b32_e32 v95, 0
	v_mov_b32_e32 v96, 0
	v_mov_b32_e32 v97, 0
	v_mov_b32_e32 v98, 0
	v_mov_b32_e32 v99, 0
	v_mov_b32_e32 v100, 0
	v_mov_b32_e32 v101, 0
	v_mov_b32_e32 v102, 0
	v_mov_b32_e32 v103, 0
	v_mov_b32_e32 v104, 0
	v_mov_b32_e32 v105, 0
	v_mov_b32_e32 v106, 0
	v_mov_b32_e32 v107, 0
	v_mov_b32_e32 v108, 0
	v_mov_b32_e32 v109, 0
	v_mov_b32_e32 v110, 0
	v_mov_b32_e32 v111, 0
	s_and_saveexec_b64 s[18:19], vcc
	global_load_dword v80, v[144:145], off
	v_lshl_add_u64 v[144:145], v[144:145], 0, s[100:101]
	global_load_dword v81, v[144:145], off
	v_lshl_add_u64 v[144:145], v[144:145], 0, s[100:101]
	global_load_dword v82, v[144:145], off
	v_lshl_add_u64 v[144:145], v[144:145], 0, s[100:101]
	global_load_dword v83, v[144:145], off
	v_lshl_add_u64 v[144:145], v[144:145], 0, s[100:101]
	global_load_dword v84, v[144:145], off
	v_lshl_add_u64 v[144:145], v[144:145], 0, s[100:101]
	global_load_dword v85, v[144:145], off
	v_lshl_add_u64 v[144:145], v[144:145], 0, s[100:101]
	global_load_dword v86, v[144:145], off
	v_lshl_add_u64 v[144:145], v[144:145], 0, s[100:101]
	global_load_dword v87, v[144:145], off
	v_lshl_add_u64 v[144:145], v[144:145], 0, s[100:101]
	global_load_dword v88, v[144:145], off
	v_lshl_add_u64 v[144:145], v[144:145], 0, s[100:101]
	global_load_dword v89, v[144:145], off
	v_lshl_add_u64 v[144:145], v[144:145], 0, s[100:101]
	global_load_dword v90, v[144:145], off
	v_lshl_add_u64 v[144:145], v[144:145], 0, s[100:101]
	global_load_dword v91, v[144:145], off
	v_lshl_add_u64 v[144:145], v[144:145], 0, s[100:101]
	global_load_dword v92, v[144:145], off
	v_lshl_add_u64 v[144:145], v[144:145], 0, s[100:101]
	global_load_dword v93, v[144:145], off
	v_lshl_add_u64 v[144:145], v[144:145], 0, s[100:101]
	global_load_dword v94, v[144:145], off
	v_lshl_add_u64 v[144:145], v[144:145], 0, s[100:101]
	global_load_dword v95, v[144:145], off
	v_lshl_add_u64 v[144:145], v[144:145], 0, s[100:101]
	global_load_dword v96, v[144:145], off
	v_lshl_add_u64 v[144:145], v[144:145], 0, s[100:101]
	global_load_dword v97, v[144:145], off
	v_lshl_add_u64 v[144:145], v[144:145], 0, s[100:101]
	global_load_dword v98, v[144:145], off
	v_lshl_add_u64 v[144:145], v[144:145], 0, s[100:101]
	global_load_dword v99, v[144:145], off
	v_lshl_add_u64 v[144:145], v[144:145], 0, s[100:101]
	global_load_dword v100, v[144:145], off
	v_lshl_add_u64 v[144:145], v[144:145], 0, s[100:101]
	global_load_dword v101, v[144:145], off
	v_lshl_add_u64 v[144:145], v[144:145], 0, s[100:101]
	global_load_dword v102, v[144:145], off
	v_lshl_add_u64 v[144:145], v[144:145], 0, s[100:101]
	global_load_dword v103, v[144:145], off
	v_lshl_add_u64 v[144:145], v[144:145], 0, s[100:101]
	global_load_dword v104, v[144:145], off
	v_lshl_add_u64 v[144:145], v[144:145], 0, s[100:101]
	global_load_dword v105, v[144:145], off
	v_lshl_add_u64 v[144:145], v[144:145], 0, s[100:101]
	global_load_dword v106, v[144:145], off
	v_lshl_add_u64 v[144:145], v[144:145], 0, s[100:101]
	global_load_dword v107, v[144:145], off
	v_lshl_add_u64 v[144:145], v[144:145], 0, s[100:101]
	global_load_dword v108, v[144:145], off
	v_lshl_add_u64 v[144:145], v[144:145], 0, s[100:101]
	global_load_dword v109, v[144:145], off
	v_lshl_add_u64 v[144:145], v[144:145], 0, s[100:101]
	global_load_dword v110, v[144:145], off
	v_lshl_add_u64 v[144:145], v[144:145], 0, s[100:101]
	global_load_dword v111, v[144:145], off
	s_or_b64 exec, exec, s[18:19]
	s_waitcnt vmcnt(24)
	ds_write_b32 v5, v80 offset:0
	ds_write_b32 v5, v81 offset:264
	ds_write_b32 v5, v82 offset:528
	ds_write_b32 v5, v83 offset:792
	ds_write_b32 v5, v84 offset:1056
	ds_write_b32 v5, v85 offset:1320
	ds_write_b32 v5, v86 offset:1584
	ds_write_b32 v5, v87 offset:1848
	s_waitcnt vmcnt(16)
	ds_write_b32 v5, v88 offset:2112
	ds_write_b32 v5, v89 offset:2376
	ds_write_b32 v5, v90 offset:2640
	ds_write_b32 v5, v91 offset:2904
	ds_write_b32 v5, v92 offset:3168
	ds_write_b32 v5, v93 offset:3432
	ds_write_b32 v5, v94 offset:3696
	ds_write_b32 v5, v95 offset:3960
	s_waitcnt vmcnt(8)
	ds_write_b32 v5, v96 offset:4224
	ds_write_b32 v5, v97 offset:4488
	ds_write_b32 v5, v98 offset:4752
	ds_write_b32 v5, v99 offset:5016
	ds_write_b32 v5, v100 offset:5280
	ds_write_b32 v5, v101 offset:5544
	ds_write_b32 v5, v102 offset:5808
	ds_write_b32 v5, v103 offset:6072
	s_waitcnt vmcnt(0)
	ds_write_b32 v5, v104 offset:6336
	ds_write_b32 v5, v105 offset:6600
	ds_write_b32 v5, v106 offset:6864
	ds_write_b32 v5, v107 offset:7128
	ds_write_b32 v5, v108 offset:7392
	ds_write_b32 v5, v109 offset:7656
	ds_write_b32 v5, v110 offset:7920
	ds_write_b32 v5, v111 offset:8184

.LBB0_1529:
	v_mul_hi_i32 v0, v19, s5
	v_lshrrev_b32_e32 v1, 31, v0
	v_ashrrev_i32_e32 v0, 4, v0
	v_add_u32_e32 v0, v0, v1
	v_mul_lo_u32 v1, v0, s30
	v_sub_u32_e32 v26, v19, v1
	v_lshlrev_b32_e32 v8, 6, v0
	v_lshlrev_b32_e32 v25, 5, v26
	v_or_b32_e32 v0, v25, v5
	v_ashrrev_i32_e32 v9, 31, v8
	v_ashrrev_i32_e32 v1, 31, v0
	v_or_b32_e32 v2, v4, v8
	v_mov_b32_e32 v3, v9
	v_cmp_gt_i32_e64 s[10:11], s31, v0
	v_lshl_add_u64 v[0:1], v[0:1], 2, s[14:15]
	v_lshl_add_u64 v[10:11], v[2:3], 2, s[26:27]
	v_mov_b32_e32 v3, v24
	v_mad_u64_u32 v[144:145], vcc, v2, s34, v[0:1]
	s_mov_b64 s[100:101], 0x5800
	v_mov_b32_e32 v80, 0
	v_mov_b32_e32 v81, 0
	v_mov_b32_e32 v82, 0
	v_mov_b32_e32 v83, 0
	v_mov_b32_e32 v84, 0
	v_mov_b32_e32 v85, 0
	v_mov_b32_e32 v86, 0
	v_mov_b32_e32 v87, 0
	v_mov_b32_e32 v88, 0
	v_mov_b32_e32 v89, 0
	v_mov_b32_e32 v90, 0
	v_mov_b32_e32 v91, 0
	v_mov_b32_e32 v92, 0
	v_mov_b32_e32 v93, 0
	v_mov_b32_e32 v94, 0
	v_mov_b32_e32 v95, 0
	v_mov_b32_e32 v96, 0
	v_mov_b32_e32 v97, 0
	v_mov_b32_e32 v98, 0
	v_mov_b32_e32 v99, 0
	v_mov_b32_e32 v100, 0
	v_mov_b32_e32 v101, 0
	v_mov_b32_e32 v102, 0
	v_mov_b32_e32 v103, 0
	v_mov_b32_e32 v104, 0
	v_mov_b32_e32 v105, 0
	v_mov_b32_e32 v106, 0
	v_mov_b32_e32 v107, 0
	v_mov_b32_e32 v108, 0
	v_mov_b32_e32 v109, 0
	v_mov_b32_e32 v110, 0
	v_mov_b32_e32 v111, 0
	s_and_saveexec_b64 s[28:29], s[10:11]
	global_load_dword v80, v[144:145], off
	v_lshl_add_u64 v[144:145], v[144:145], 0, s[100:101]
	global_load_dword v81, v[144:145], off
	v_lshl_add_u64 v[144:145], v[144:145], 0, s[100:101]
	global_load_dword v82, v[144:145], off
	v_lshl_add_u64 v[144:145], v[144:145], 0, s[100:101]
	global_load_dword v83, v[144:145], off
	v_lshl_add_u64 v[144:145], v[144:145], 0, s[100:101]
	global_load_dword v84, v[144:145], off
	v_lshl_add_u64 v[144:145], v[144:145], 0, s[100:101]
	global_load_dword v85, v[144:145], off
	v_lshl_add_u64 v[144:145], v[144:145], 0, s[100:101]
	global_load_dword v86, v[144:145], off
	v_lshl_add_u64 v[144:145], v[144:145], 0, s[100:101]
	global_load_dword v87, v[144:145], off
	v_lshl_add_u64 v[144:145], v[144:145], 0, s[100:101]
	global_load_dword v88, v[144:145], off
	v_lshl_add_u64 v[144:145], v[144:145], 0, s[100:101]
	global_load_dword v89, v[144:145], off
	v_lshl_add_u64 v[144:145], v[144:145], 0, s[100:101]
	global_load_dword v90, v[144:145], off
	v_lshl_add_u64 v[144:145], v[144:145], 0, s[100:101]
	global_load_dword v91, v[144:145], off
	v_lshl_add_u64 v[144:145], v[144:145], 0, s[100:101]
	global_load_dword v92, v[144:145], off
	v_lshl_add_u64 v[144:145], v[144:145], 0, s[100:101]
	global_load_dword v93, v[144:145], off
	v_lshl_add_u64 v[144:145], v[144:145], 0, s[100:101]
	global_load_dword v94, v[144:145], off
	v_lshl_add_u64 v[144:145], v[144:145], 0, s[100:101]
	global_load_dword v95, v[144:145], off
	v_lshl_add_u64 v[144:145], v[144:145], 0, s[100:101]
	global_load_dword v96, v[144:145], off
	v_lshl_add_u64 v[144:145], v[144:145], 0, s[100:101]
	global_load_dword v97, v[144:145], off
	v_lshl_add_u64 v[144:145], v[144:145], 0, s[100:101]
	global_load_dword v98, v[144:145], off
	v_lshl_add_u64 v[144:145], v[144:145], 0, s[100:101]
	global_load_dword v99, v[144:145], off
	v_lshl_add_u64 v[144:145], v[144:145], 0, s[100:101]
	global_load_dword v100, v[144:145], off
	v_lshl_add_u64 v[144:145], v[144:145], 0, s[100:101]
	global_load_dword v101, v[144:145], off
	v_lshl_add_u64 v[144:145], v[144:145], 0, s[100:101]
	global_load_dword v102, v[144:145], off
	v_lshl_add_u64 v[144:145], v[144:145], 0, s[100:101]
	global_load_dword v103, v[144:145], off
	v_lshl_add_u64 v[144:145], v[144:145], 0, s[100:101]
	global_load_dword v104, v[144:145], off
	v_lshl_add_u64 v[144:145], v[144:145], 0, s[100:101]
	global_load_dword v105, v[144:145], off
	v_lshl_add_u64 v[144:145], v[144:145], 0, s[100:101]
	global_load_dword v106, v[144:145], off
	v_lshl_add_u64 v[144:145], v[144:145], 0, s[100:101]
	global_load_dword v107, v[144:145], off
	v_lshl_add_u64 v[144:145], v[144:145], 0, s[100:101]
	global_load_dword v108, v[144:145], off
	v_lshl_add_u64 v[144:145], v[144:145], 0, s[100:101]
	global_load_dword v109, v[144:145], off
	v_lshl_add_u64 v[144:145], v[144:145], 0, s[100:101]
	global_load_dword v110, v[144:145], off
	v_lshl_add_u64 v[144:145], v[144:145], 0, s[100:101]
	global_load_dword v111, v[144:145], off
	s_or_b64 exec, exec, s[28:29]
	s_and_b64 vcc, exec, s[8:9]
	s_cbranch_vccnz .Ltr_nogain_2
	v_cmp_gt_i32_e32 vcc, s35, v2
	s_and_saveexec_b64 s[28:29], vcc
	v_mov_b32_e32 v146, v2
	v_mov_b32_e32 v147, 0
	v_lshl_add_u64 v[146:147], v[146:147], 2, s[12:13]
	global_load_dword v112, v[146:147], off offset:0
	global_load_dword v113, v[146:147], off offset:8
	global_load_dword v114, v[146:147], off offset:16
	global_load_dword v115, v[146:147], off offset:24
	global_load_dword v116, v[146:147], off offset:32
	global_load_dword v117, v[146:147], off offset:40
	global_load_dword v118, v[146:147], off offset:48
	global_load_dword v119, v[146:147], off offset:56
	global_load_dword v120, v[146:147], off offset:64
	global_load_dword v121, v[146:147], off offset:72
	global_load_dword v122, v[146:147], off offset:80
	global_load_dword v123, v[146:147], off offset:88
	global_load_dword v124, v[146:147], off offset:96
	global_load_dword v125, v[146:147], off offset:104
	global_load_dword v126, v[146:147], off offset:112
	global_load_dword v127, v[146:147], off offset:120
	global_load_dword v128, v[146:147], off offset:128
	global_load_dword v129, v[146:147], off offset:136
	global_load_dword v130, v[146:147], off offset:144
	global_load_dword v131, v[146:147], off offset:152
	global_load_dword v132, v[146:147], off offset:160
	global_load_dword v133, v[146:147], off offset:168
	global_load_dword v134, v[146:147], off offset:176
	global_load_dword v135, v[146:147], off offset:184
	global_load_dword v136, v[146:147], off offset:192
	global_load_dword v137, v[146:147], off offset:200
	global_load_dword v138, v[146:147], off offset:208
	global_load_dword v139, v[146:147], off offset:216
	global_load_dword v140, v[146:147], off offset:224
	global_load_dword v141, v[146:147], off offset:232
	global_load_dword v142, v[146:147], off offset:240
	global_load_dword v143, v[146:147], off offset:248
	s_waitcnt vmcnt(0)
	v_mul_f32_e32 v80, v80, v112
	v_mul_f32_e32 v81, v81, v113
	v_mul_f32_e32 v82, v82, v114
	v_mul_f32_e32 v83, v83, v115
	v_mul_f32_e32 v84, v84, v116
	v_mul_f32_e32 v85, v85, v117
	v_mul_f32_e32 v86, v86, v118
	v_mul_f32_e32 v87, v87, v119
	v_mul_f32_e32 v88, v88, v120
	v_mul_f32_e32 v89, v89, v121
	v_mul_f32_e32 v90, v90, v122
	v_mul_f32_e32 v91, v91, v123
	v_mul_f32_e32 v92, v92, v124
	v_mul_f32_e32 v93, v93, v125
	v_mul_f32_e32 v94, v94, v126
	v_mul_f32_e32 v95, v95, v127
	v_mul_f32_e32 v96, v96, v128
	v_mul_f32_e32 v97, v97, v129
	v_mul_f32_e32 v98, v98, v130
	v_mul_f32_e32 v99, v99, v131
	v_mul_f32_e32 v100, v100, v132
	v_mul_f32_e32 v101, v101, v133
	v_mul_f32_e32 v102, v102, v134
	v_mul_f32_e32 v103, v103, v135
	v_mul_f32_e32 v104, v104, v136
	v_mul_f32_e32 v105, v105, v137
	v_mul_f32_e32 v106, v106, v138
	v_mul_f32_e32 v107, v107, v139
	v_mul_f32_e32 v108, v108, v140
	v_mul_f32_e32 v109, v109, v141
	v_mul_f32_e32 v110, v110, v142
	v_mul_f32_e32 v111, v111, v143
	s_or_b64 exec, exec, s[28:29]
.Ltr_nogain_2:
	s_waitcnt vmcnt(24)
	ds_write_b32 v3, v80 offset:0
	ds_write_b32 v3, v81 offset:264
	ds_write_b32 v3, v82 offset:528
	ds_write_b32 v3, v83 offset:792
	ds_write_b32 v3, v84 offset:1056
	ds_write_b32 v3, v85 offset:1320
	ds_write_b32 v3, v86 offset:1584
	ds_write_b32 v3, v87 offset:1848
	s_waitcnt vmcnt(16)
	ds_write_b32 v3, v88 offset:2112
	ds_write_b32 v3, v89 offset:2376
	ds_write_b32 v3, v90 offset:2640
	ds_write_b32 v3, v91 offset:2904
	ds_write_b32 v3, v92 offset:3168
	ds_write_b32 v3, v93 offset:3432
	ds_write_b32 v3, v94 offset:3696
	ds_write_b32 v3, v95 offset:3960
	s_waitcnt vmcnt(8)
	ds_write_b32 v3, v96 offset:4224
	ds_write_b32 v3, v97 offset:4488
	ds_write_b32 v3, v98 offset:4752
	ds_write_b32 v3, v99 offset:5016
	ds_write_b32 v3, v100 offset:5280
	ds_write_b32 v3, v101 offset:5544
	ds_write_b32 v3, v102 offset:5808
	ds_write_b32 v3, v103 offset:6072
	s_waitcnt vmcnt(0)
	ds_write_b32 v3, v104 offset:6336
	ds_write_b32 v3, v105 offset:6600
	ds_write_b32 v3, v106 offset:6864
	ds_write_b32 v3, v107 offset:7128
	ds_write_b32 v3, v108 offset:7392
	ds_write_b32 v3, v109 offset:7656
	ds_write_b32 v3, v110 offset:7920
	ds_write_b32 v3, v111 offset:8184

.LBB0_1590:
	v_mul_hi_i32 v0, v19, s31
	v_lshrrev_b32_e32 v1, 31, v0
	v_ashrrev_i32_e32 v0, 4, v0
	v_add_u32_e32 v0, v0, v1
	v_mul_lo_u32 v1, v0, s34
	v_sub_u32_e32 v26, v19, v1
	v_lshlrev_b32_e32 v8, 6, v0
	v_lshlrev_b32_e32 v25, 5, v26
	v_or_b32_e32 v0, v25, v5
	v_ashrrev_i32_e32 v9, 31, v8
	v_ashrrev_i32_e32 v1, 31, v0
	v_or_b32_e32 v2, v4, v8
	v_mov_b32_e32 v3, v9
	v_cmp_gt_i32_e64 s[10:11], s35, v0
	v_lshl_add_u64 v[0:1], v[0:1], 2, s[22:23]
	v_lshl_add_u64 v[10:11], v[2:3], 2, s[26:27]
	v_mov_b32_e32 v3, v24
	v_mad_u64_u32 v[144:145], vcc, v2, s36, v[0:1]
	s_mov_b64 s[100:101], 0x5800
	v_mov_b32_e32 v80, 0
	v_mov_b32_e32 v81, 0
	v_mov_b32_e32 v82, 0
	v_mov_b32_e32 v83, 0
	v_mov_b32_e32 v84, 0
	v_mov_b32_e32 v85, 0
	v_mov_b32_e32 v86, 0
	v_mov_b32_e32 v87, 0
	v_mov_b32_e32 v88, 0
	v_mov_b32_e32 v89, 0
	v_mov_b32_e32 v90, 0
	v_mov_b32_e32 v91, 0
	v_mov_b32_e32 v92, 0
	v_mov_b32_e32 v93, 0
	v_mov_b32_e32 v94, 0
	v_mov_b32_e32 v95, 0
	v_mov_b32_e32 v96, 0
	v_mov_b32_e32 v97, 0
	v_mov_b32_e32 v98, 0
	v_mov_b32_e32 v99, 0
	v_mov_b32_e32 v100, 0
	v_mov_b32_e32 v101, 0
	v_mov_b32_e32 v102, 0
	v_mov_b32_e32 v103, 0
	v_mov_b32_e32 v104, 0
	v_mov_b32_e32 v105, 0
	v_mov_b32_e32 v106, 0
	v_mov_b32_e32 v107, 0
	v_mov_b32_e32 v108, 0
	v_mov_b32_e32 v109, 0
	v_mov_b32_e32 v110, 0
	v_mov_b32_e32 v111, 0
	s_and_saveexec_b64 s[28:29], s[10:11]
	global_load_dword v80, v[144:145], off
	v_lshl_add_u64 v[144:145], v[144:145], 0, s[100:101]
	global_load_dword v81, v[144:145], off
	v_lshl_add_u64 v[144:145], v[144:145], 0, s[100:101]
	global_load_dword v82, v[144:145], off
	v_lshl_add_u64 v[144:145], v[144:145], 0, s[100:101]
	global_load_dword v83, v[144:145], off
	v_lshl_add_u64 v[144:145], v[144:145], 0, s[100:101]
	global_load_dword v84, v[144:145], off
	v_lshl_add_u64 v[144:145], v[144:145], 0, s[100:101]
	global_load_dword v85, v[144:145], off
	v_lshl_add_u64 v[144:145], v[144:145], 0, s[100:101]
	global_load_dword v86, v[144:145], off
	v_lshl_add_u64 v[144:145], v[144:145], 0, s[100:101]
	global_load_dword v87, v[144:145], off
	v_lshl_add_u64 v[144:145], v[144:145], 0, s[100:101]
	global_load_dword v88, v[144:145], off
	v_lshl_add_u64 v[144:145], v[144:145], 0, s[100:101]
	global_load_dword v89, v[144:145], off
	v_lshl_add_u64 v[144:145], v[144:145], 0, s[100:101]
	global_load_dword v90, v[144:145], off
	v_lshl_add_u64 v[144:145], v[144:145], 0, s[100:101]
	global_load_dword v91, v[144:145], off
	v_lshl_add_u64 v[144:145], v[144:145], 0, s[100:101]
	global_load_dword v92, v[144:145], off
	v_lshl_add_u64 v[144:145], v[144:145], 0, s[100:101]
	global_load_dword v93, v[144:145], off
	v_lshl_add_u64 v[144:145], v[144:145], 0, s[100:101]
	global_load_dword v94, v[144:145], off
	v_lshl_add_u64 v[144:145], v[144:145], 0, s[100:101]
	global_load_dword v95, v[144:145], off
	v_lshl_add_u64 v[144:145], v[144:145], 0, s[100:101]
	global_load_dword v96, v[144:145], off
	v_lshl_add_u64 v[144:145], v[144:145], 0, s[100:101]
	global_load_dword v97, v[144:145], off
	v_lshl_add_u64 v[144:145], v[144:145], 0, s[100:101]
	global_load_dword v98, v[144:145], off
	v_lshl_add_u64 v[144:145], v[144:145], 0, s[100:101]
	global_load_dword v99, v[144:145], off
	v_lshl_add_u64 v[144:145], v[144:145], 0, s[100:101]
	global_load_dword v100, v[144:145], off
	v_lshl_add_u64 v[144:145], v[144:145], 0, s[100:101]
	global_load_dword v101, v[144:145], off
	v_lshl_add_u64 v[144:145], v[144:145], 0, s[100:101]
	global_load_dword v102, v[144:145], off
	v_lshl_add_u64 v[144:145], v[144:145], 0, s[100:101]
	global_load_dword v103, v[144:145], off
	v_lshl_add_u64 v[144:145], v[144:145], 0, s[100:101]
	global_load_dword v104, v[144:145], off
	v_lshl_add_u64 v[144:145], v[144:145], 0, s[100:101]
	global_load_dword v105, v[144:145], off
	v_lshl_add_u64 v[144:145], v[144:145], 0, s[100:101]
	global_load_dword v106, v[144:145], off
	v_lshl_add_u64 v[144:145], v[144:145], 0, s[100:101]
	global_load_dword v107, v[144:145], off
	v_lshl_add_u64 v[144:145], v[144:145], 0, s[100:101]
	global_load_dword v108, v[144:145], off
	v_lshl_add_u64 v[144:145], v[144:145], 0, s[100:101]
	global_load_dword v109, v[144:145], off
	v_lshl_add_u64 v[144:145], v[144:145], 0, s[100:101]
	global_load_dword v110, v[144:145], off
	v_lshl_add_u64 v[144:145], v[144:145], 0, s[100:101]
	global_load_dword v111, v[144:145], off
	s_or_b64 exec, exec, s[28:29]
	s_and_b64 vcc, exec, s[8:9]
	s_cbranch_vccnz .Ltr_nogain_3
	v_cmp_gt_i32_e32 vcc, s37, v2
	s_and_saveexec_b64 s[28:29], vcc
	v_mov_b32_e32 v146, v2
	v_mov_b32_e32 v147, 0
	v_lshl_add_u64 v[146:147], v[146:147], 2, s[14:15]
	global_load_dword v112, v[146:147], off offset:0
	global_load_dword v113, v[146:147], off offset:8
	global_load_dword v114, v[146:147], off offset:16
	global_load_dword v115, v[146:147], off offset:24
	global_load_dword v116, v[146:147], off offset:32
	global_load_dword v117, v[146:147], off offset:40
	global_load_dword v118, v[146:147], off offset:48
	global_load_dword v119, v[146:147], off offset:56
	global_load_dword v120, v[146:147], off offset:64
	global_load_dword v121, v[146:147], off offset:72
	global_load_dword v122, v[146:147], off offset:80
	global_load_dword v123, v[146:147], off offset:88
	global_load_dword v124, v[146:147], off offset:96
	global_load_dword v125, v[146:147], off offset:104
	global_load_dword v126, v[146:147], off offset:112
	global_load_dword v127, v[146:147], off offset:120
	global_load_dword v128, v[146:147], off offset:128
	global_load_dword v129, v[146:147], off offset:136
	global_load_dword v130, v[146:147], off offset:144
	global_load_dword v131, v[146:147], off offset:152
	global_load_dword v132, v[146:147], off offset:160
	global_load_dword v133, v[146:147], off offset:168
	global_load_dword v134, v[146:147], off offset:176
	global_load_dword v135, v[146:147], off offset:184
	global_load_dword v136, v[146:147], off offset:192
	global_load_dword v137, v[146:147], off offset:200
	global_load_dword v138, v[146:147], off offset:208
	global_load_dword v139, v[146:147], off offset:216
	global_load_dword v140, v[146:147], off offset:224
	global_load_dword v141, v[146:147], off offset:232
	global_load_dword v142, v[146:147], off offset:240
	global_load_dword v143, v[146:147], off offset:248
	s_waitcnt vmcnt(0)
	v_mul_f32_e32 v80, v80, v112
	v_mul_f32_e32 v81, v81, v113
	v_mul_f32_e32 v82, v82, v114
	v_mul_f32_e32 v83, v83, v115
	v_mul_f32_e32 v84, v84, v116
	v_mul_f32_e32 v85, v85, v117
	v_mul_f32_e32 v86, v86, v118
	v_mul_f32_e32 v87, v87, v119
	v_mul_f32_e32 v88, v88, v120
	v_mul_f32_e32 v89, v89, v121
	v_mul_f32_e32 v90, v90, v122
	v_mul_f32_e32 v91, v91, v123
	v_mul_f32_e32 v92, v92, v124
	v_mul_f32_e32 v93, v93, v125
	v_mul_f32_e32 v94, v94, v126
	v_mul_f32_e32 v95, v95, v127
	v_mul_f32_e32 v96, v96, v128
	v_mul_f32_e32 v97, v97, v129
	v_mul_f32_e32 v98, v98, v130
	v_mul_f32_e32 v99, v99, v131
	v_mul_f32_e32 v100, v100, v132
	v_mul_f32_e32 v101, v101, v133
	v_mul_f32_e32 v102, v102, v134
	v_mul_f32_e32 v103, v103, v135
	v_mul_f32_e32 v104, v104, v136
	v_mul_f32_e32 v105, v105, v137
	v_mul_f32_e32 v106, v106, v138
	v_mul_f32_e32 v107, v107, v139
	v_mul_f32_e32 v108, v108, v140
	v_mul_f32_e32 v109, v109, v141
	v_mul_f32_e32 v110, v110, v142
	v_mul_f32_e32 v111, v111, v143
	s_or_b64 exec, exec, s[28:29]

.LBB0_1651:
	v_ashrrev_i32_e32 v0, 31, v10
	v_lshrrev_b32_e32 v0, 27, v0
	v_add_u32_e32 v0, v10, v0
	v_and_b32_e32 v1, 0x7ffffe0, v0
	v_sub_u32_e32 v1, v10, v1
	v_lshlrev_b32_e32 v0, 1, v0
	v_lshlrev_b32_e32 v21, 5, v1
	v_and_b32_e32 v8, 0xffffffc0, v0
	v_or_b32_e32 v0, v21, v5
	v_ashrrev_i32_e32 v1, 31, v0
	v_cmp_gt_i32_e32 vcc, s23, v0
	v_lshl_add_u64 v[0:1], v[0:1], 2, s[10:11]
	v_or_b32_e32 v2, v4, v8
	v_mov_b32_e32 v3, v20
	v_mov_b32_e32 v144, v2
	v_mov_b32_e32 v145, 0
	v_lshlrev_b64 v[144:145], 12, v[144:145]
	v_lshl_add_u64 v[144:145], v[0:1], 0, v[144:145]
	s_mov_b64 s[100:101], 0x2000
	v_mov_b32_e32 v80, 0
	v_mov_b32_e32 v81, 0
	v_mov_b32_e32 v82, 0
	v_mov_b32_e32 v83, 0
	v_mov_b32_e32 v84, 0
	v_mov_b32_e32 v85, 0
	v_mov_b32_e32 v86, 0
	v_mov_b32_e32 v87, 0
	v_mov_b32_e32 v88, 0
	v_mov_b32_e32 v89, 0
	v_mov_b32_e32 v90, 0
	v_mov_b32_e32 v91, 0
	v_mov_b32_e32 v92, 0
	v_mov_b32_e32 v93, 0
	v_mov_b32_e32 v94, 0
	v_mov_b32_e32 v95, 0
	v_mov_b32_e32 v96, 0
	v_mov_b32_e32 v97, 0
	v_mov_b32_e32 v98, 0
	v_mov_b32_e32 v99, 0
	v_mov_b32_e32 v100, 0
	v_mov_b32_e32 v101, 0
	v_mov_b32_e32 v102, 0
	v_mov_b32_e32 v103, 0
	v_mov_b32_e32 v104, 0
	v_mov_b32_e32 v105, 0
	v_mov_b32_e32 v106, 0
	v_mov_b32_e32 v107, 0
	v_mov_b32_e32 v108, 0
	v_mov_b32_e32 v109, 0
	v_mov_b32_e32 v110, 0
	v_mov_b32_e32 v111, 0
	s_and_saveexec_b64 s[14:15], vcc
	global_load_dword v80, v[144:145], off
	v_lshl_add_u64 v[144:145], v[144:145], 0, s[100:101]
	global_load_dword v81, v[144:145], off
	v_lshl_add_u64 v[144:145], v[144:145], 0, s[100:101]
	global_load_dword v82, v[144:145], off
	v_lshl_add_u64 v[144:145], v[144:145], 0, s[100:101]
	global_load_dword v83, v[144:145], off
	v_lshl_add_u64 v[144:145], v[144:145], 0, s[100:101]
	global_load_dword v84, v[144:145], off
	v_lshl_add_u64 v[144:145], v[144:145], 0, s[100:101]
	global_load_dword v85, v[144:145], off
	v_lshl_add_u64 v[144:145], v[144:145], 0, s[100:101]
	global_load_dword v86, v[144:145], off
	v_lshl_add_u64 v[144:145], v[144:145], 0, s[100:101]
	global_load_dword v87, v[144:145], off
	v_lshl_add_u64 v[144:145], v[144:145], 0, s[100:101]
	global_load_dword v88, v[144:145], off
	v_lshl_add_u64 v[144:145], v[144:145], 0, s[100:101]
	global_load_dword v89, v[144:145], off
	v_lshl_add_u64 v[144:145], v[144:145], 0, s[100:101]
	global_load_dword v90, v[144:145], off
	v_lshl_add_u64 v[144:145], v[144:145], 0, s[100:101]
	global_load_dword v91, v[144:145], off
	v_lshl_add_u64 v[144:145], v[144:145], 0, s[100:101]
	global_load_dword v92, v[144:145], off
	v_lshl_add_u64 v[144:145], v[144:145], 0, s[100:101]
	global_load_dword v93, v[144:145], off
	v_lshl_add_u64 v[144:145], v[144:145], 0, s[100:101]
	global_load_dword v94, v[144:145], off
	v_lshl_add_u64 v[144:145], v[144:145], 0, s[100:101]
	global_load_dword v95, v[144:145], off
	v_lshl_add_u64 v[144:145], v[144:145], 0, s[100:101]
	global_load_dword v96, v[144:145], off
	v_lshl_add_u64 v[144:145], v[144:145], 0, s[100:101]
	global_load_dword v97, v[144:145], off
	v_lshl_add_u64 v[144:145], v[144:145], 0, s[100:101]
	global_load_dword v98, v[144:145], off
	v_lshl_add_u64 v[144:145], v[144:145], 0, s[100:101]
	global_load_dword v99, v[144:145], off
	v_lshl_add_u64 v[144:145], v[144:145], 0, s[100:101]
	global_load_dword v100, v[144:145], off
	v_lshl_add_u64 v[144:145], v[144:145], 0, s[100:101]
	global_load_dword v101, v[144:145], off
	v_lshl_add_u64 v[144:145], v[144:145], 0, s[100:101]
	global_load_dword v102, v[144:145], off
	v_lshl_add_u64 v[144:145], v[144:145], 0, s[100:101]
	global_load_dword v103, v[144:145], off
	v_lshl_add_u64 v[144:145], v[144:145], 0, s[100:101]
	global_load_dword v104, v[144:145], off
	v_lshl_add_u64 v[144:145], v[144:145], 0, s[100:101]
	global_load_dword v105, v[144:145], off
	v_lshl_add_u64 v[144:145], v[144:145], 0, s[100:101]
	global_load_dword v106, v[144:145], off
	v_lshl_add_u64 v[144:145], v[144:145], 0, s[100:101]
	global_load_dword v107, v[144:145], off
	v_lshl_add_u64 v[144:145], v[144:145], 0, s[100:101]
	global_load_dword v108, v[144:145], off
	v_lshl_add_u64 v[144:145], v[144:145], 0, s[100:101]
	global_load_dword v109, v[144:145], off
	v_lshl_add_u64 v[144:145], v[144:145], 0, s[100:101]
	global_load_dword v110, v[144:145], off
	v_lshl_add_u64 v[144:145], v[144:145], 0, s[100:101]
	global_load_dword v111, v[144:145], off
	s_or_b64 exec, exec, s[14:15]
	s_waitcnt vmcnt(24)
	ds_write_b32 v3, v80 offset:0
	ds_write_b32 v3, v81 offset:264
	ds_write_b32 v3, v82 offset:528
	ds_write_b32 v3, v83 offset:792
	ds_write_b32 v3, v84 offset:1056
	ds_write_b32 v3, v85 offset:1320
	ds_write_b32 v3, v86 offset:1584
	ds_write_b32 v3, v87 offset:1848
	s_waitcnt vmcnt(16)
	ds_write_b32 v3, v88 offset:2112
	ds_write_b32 v3, v89 offset:2376
	ds_write_b32 v3, v90 offset:2640
	ds_write_b32 v3, v91 offset:2904
	ds_write_b32 v3, v92 offset:3168
	ds_write_b32 v3, v93 offset:3432
	ds_write_b32 v3, v94 offset:3696
	ds_write_b32 v3, v95 offset:3960
	s_waitcnt vmcnt(8)
	ds_write_b32 v3, v96 offset:4224
	ds_write_b32 v3, v97 offset:4488
	ds_write_b32 v3, v98 offset:4752
	ds_write_b32 v3, v99 offset:5016
	ds_write_b32 v3, v100 offset:5280
	ds_write_b32 v3, v101 offset:5544
	ds_write_b32 v3, v102 offset:5808
	ds_write_b32 v3, v103 offset:6072
	s_waitcnt vmcnt(0)
	ds_write_b32 v3, v104 offset:6336
	ds_write_b32 v3, v105 offset:6600
	ds_write_b32 v3, v106 offset:6864
	ds_write_b32 v3, v107 offset:7128
	ds_write_b32 v3, v108 offset:7392
	ds_write_b32 v3, v109 offset:7656
	ds_write_b32 v3, v110 offset:7920
	ds_write_b32 v3, v111 offset:8184

.LBB0_1680:
	v_ashrrev_i32_e32 v0, 31, v19
	v_lshrrev_b32_e32 v0, 27, v0
	v_add_u32_e32 v0, v19, v0
	v_and_b32_e32 v1, 0x7ffffe0, v0
	v_sub_u32_e32 v1, v19, v1
	v_lshlrev_b32_e32 v0, 1, v0
	v_and_b32_e32 v8, 0xffffffc0, v0
	v_lshlrev_b32_e32 v25, 5, v1
	v_or_b32_e32 v0, v25, v5
	v_ashrrev_i32_e32 v9, 31, v8
	v_ashrrev_i32_e32 v1, 31, v0
	v_or_b32_e32 v2, v4, v8
	v_mov_b32_e32 v3, v9
	v_cmp_gt_i32_e64 s[10:11], s31, v0
	v_lshl_add_u64 v[0:1], v[0:1], 2, s[14:15]
	v_lshl_add_u64 v[10:11], v[2:3], 2, s[26:27]
	v_mov_b32_e32 v3, v24
	v_mov_b32_e32 v144, v2
	v_mov_b32_e32 v145, 0
	v_lshlrev_b64 v[144:145], 12, v[144:145]
	v_lshl_add_u64 v[144:145], v[0:1], 0, v[144:145]
	s_mov_b64 s[100:101], 0x2000
	v_mov_b32_e32 v80, 0
	v_mov_b32_e32 v81, 0
	v_mov_b32_e32 v82, 0
	v_mov_b32_e32 v83, 0
	v_mov_b32_e32 v84, 0
	v_mov_b32_e32 v85, 0
	v_mov_b32_e32 v86, 0
	v_mov_b32_e32 v87, 0
	v_mov_b32_e32 v88, 0
	v_mov_b32_e32 v89, 0
	v_mov_b32_e32 v90, 0
	v_mov_b32_e32 v91, 0
	v_mov_b32_e32 v92, 0
	v_mov_b32_e32 v93, 0
	v_mov_b32_e32 v94, 0
	v_mov_b32_e32 v95, 0
	v_mov_b32_e32 v96, 0
	v_mov_b32_e32 v97, 0
	v_mov_b32_e32 v98, 0
	v_mov_b32_e32 v99, 0
	v_mov_b32_e32 v100, 0
	v_mov_b32_e32 v101, 0
	v_mov_b32_e32 v102, 0
	v_mov_b32_e32 v103, 0
	v_mov_b32_e32 v104, 0
	v_mov_b32_e32 v105, 0
	v_mov_b32_e32 v106, 0
	v_mov_b32_e32 v107, 0
	v_mov_b32_e32 v108, 0
	v_mov_b32_e32 v109, 0
	v_mov_b32_e32 v110, 0
	v_mov_b32_e32 v111, 0
	s_and_saveexec_b64 s[28:29], s[10:11]
	global_load_dword v80, v[144:145], off
	v_lshl_add_u64 v[144:145], v[144:145], 0, s[100:101]
	global_load_dword v81, v[144:145], off
	v_lshl_add_u64 v[144:145], v[144:145], 0, s[100:101]
	global_load_dword v82, v[144:145], off
	v_lshl_add_u64 v[144:145], v[144:145], 0, s[100:101]
	global_load_dword v83, v[144:145], off
	v_lshl_add_u64 v[144:145], v[144:145], 0, s[100:101]
	global_load_dword v84, v[144:145], off
	v_lshl_add_u64 v[144:145], v[144:145], 0, s[100:101]
	global_load_dword v85, v[144:145], off
	v_lshl_add_u64 v[144:145], v[144:145], 0, s[100:101]
	global_load_dword v86, v[144:145], off
	v_lshl_add_u64 v[144:145], v[144:145], 0, s[100:101]
	global_load_dword v87, v[144:145], off
	v_lshl_add_u64 v[144:145], v[144:145], 0, s[100:101]
	global_load_dword v88, v[144:145], off
	v_lshl_add_u64 v[144:145], v[144:145], 0, s[100:101]
	global_load_dword v89, v[144:145], off
	v_lshl_add_u64 v[144:145], v[144:145], 0, s[100:101]
	global_load_dword v90, v[144:145], off
	v_lshl_add_u64 v[144:145], v[144:145], 0, s[100:101]
	global_load_dword v91, v[144:145], off
	v_lshl_add_u64 v[144:145], v[144:145], 0, s[100:101]
	global_load_dword v92, v[144:145], off
	v_lshl_add_u64 v[144:145], v[144:145], 0, s[100:101]
	global_load_dword v93, v[144:145], off
	v_lshl_add_u64 v[144:145], v[144:145], 0, s[100:101]
	global_load_dword v94, v[144:145], off
	v_lshl_add_u64 v[144:145], v[144:145], 0, s[100:101]
	global_load_dword v95, v[144:145], off
	v_lshl_add_u64 v[144:145], v[144:145], 0, s[100:101]
	global_load_dword v96, v[144:145], off
	v_lshl_add_u64 v[144:145], v[144:145], 0, s[100:101]
	global_load_dword v97, v[144:145], off
	v_lshl_add_u64 v[144:145], v[144:145], 0, s[100:101]
	global_load_dword v98, v[144:145], off
	v_lshl_add_u64 v[144:145], v[144:145], 0, s[100:101]
	global_load_dword v99, v[144:145], off
	v_lshl_add_u64 v[144:145], v[144:145], 0, s[100:101]
	global_load_dword v100, v[144:145], off
	v_lshl_add_u64 v[144:145], v[144:145], 0, s[100:101]
	global_load_dword v101, v[144:145], off
	v_lshl_add_u64 v[144:145], v[144:145], 0, s[100:101]
	global_load_dword v102, v[144:145], off
	v_lshl_add_u64 v[144:145], v[144:145], 0, s[100:101]
	global_load_dword v103, v[144:145], off
	v_lshl_add_u64 v[144:145], v[144:145], 0, s[100:101]
	global_load_dword v104, v[144:145], off
	v_lshl_add_u64 v[144:145], v[144:145], 0, s[100:101]
	global_load_dword v105, v[144:145], off
	v_lshl_add_u64 v[144:145], v[144:145], 0, s[100:101]
	global_load_dword v106, v[144:145], off
	v_lshl_add_u64 v[144:145], v[144:145], 0, s[100:101]
	global_load_dword v107, v[144:145], off
	v_lshl_add_u64 v[144:145], v[144:145], 0, s[100:101]
	global_load_dword v108, v[144:145], off
	v_lshl_add_u64 v[144:145], v[144:145], 0, s[100:101]
	global_load_dword v109, v[144:145], off
	v_lshl_add_u64 v[144:145], v[144:145], 0, s[100:101]
	global_load_dword v110, v[144:145], off
	v_lshl_add_u64 v[144:145], v[144:145], 0, s[100:101]
	global_load_dword v111, v[144:145], off
	s_or_b64 exec, exec, s[28:29]
	s_and_b64 vcc, exec, s[8:9]
	s_cbranch_vccnz .Ltr_nogain_4
	v_cmp_gt_i32_e32 vcc, s31, v2
	s_and_saveexec_b64 s[28:29], vcc
	v_mov_b32_e32 v146, v2
	v_mov_b32_e32 v147, 0
	v_lshl_add_u64 v[146:147], v[146:147], 2, s[12:13]
	global_load_dword v112, v[146:147], off offset:0
	global_load_dword v113, v[146:147], off offset:8
	global_load_dword v114, v[146:147], off offset:16
	global_load_dword v115, v[146:147], off offset:24
	global_load_dword v116, v[146:147], off offset:32
	global_load_dword v117, v[146:147], off offset:40
	global_load_dword v118, v[146:147], off offset:48
	global_load_dword v119, v[146:147], off offset:56
	global_load_dword v120, v[146:147], off offset:64
	global_load_dword v121, v[146:147], off offset:72
	global_load_dword v122, v[146:147], off offset:80
	global_load_dword v123, v[146:147], off offset:88
	global_load_dword v124, v[146:147], off offset:96
	global_load_dword v125, v[146:147], off offset:104
	global_load_dword v126, v[146:147], off offset:112
	global_load_dword v127, v[146:147], off offset:120
	global_load_dword v128, v[146:147], off offset:128
	global_load_dword v129, v[146:147], off offset:136
	global_load_dword v130, v[146:147], off offset:144
	global_load_dword v131, v[146:147], off offset:152
	global_load_dword v132, v[146:147], off offset:160
	global_load_dword v133, v[146:147], off offset:168
	global_load_dword v134, v[146:147], off offset:176
	global_load_dword v135, v[146:147], off offset:184
	global_load_dword v136, v[146:147], off offset:192
	global_load_dword v137, v[146:147], off offset:200
	global_load_dword v138, v[146:147], off offset:208
	global_load_dword v139, v[146:147], off offset:216
	global_load_dword v140, v[146:147], off offset:224
	global_load_dword v141, v[146:147], off offset:232
	global_load_dword v142, v[146:147], off offset:240
	global_load_dword v143, v[146:147], off offset:248
	s_waitcnt vmcnt(0)
	v_mul_f32_e32 v80, v80, v112
	v_mul_f32_e32 v81, v81, v113
	v_mul_f32_e32 v82, v82, v114
	v_mul_f32_e32 v83, v83, v115
	v_mul_f32_e32 v84, v84, v116
	v_mul_f32_e32 v85, v85, v117
	v_mul_f32_e32 v86, v86, v118
	v_mul_f32_e32 v87, v87, v119
	v_mul_f32_e32 v88, v88, v120
	v_mul_f32_e32 v89, v89, v121
	v_mul_f32_e32 v90, v90, v122
	v_mul_f32_e32 v91, v91, v123
	v_mul_f32_e32 v92, v92, v124
	v_mul_f32_e32 v93, v93, v125
	v_mul_f32_e32 v94, v94, v126
	v_mul_f32_e32 v95, v95, v127
	v_mul_f32_e32 v96, v96, v128
	v_mul_f32_e32 v97, v97, v129
	v_mul_f32_e32 v98, v98, v130
	v_mul_f32_e32 v99, v99, v131
	v_mul_f32_e32 v100, v100, v132
	v_mul_f32_e32 v101, v101, v133
	v_mul_f32_e32 v102, v102, v134
	v_mul_f32_e32 v103, v103, v135
	v_mul_f32_e32 v104, v104, v136
	v_mul_f32_e32 v105, v105, v137
	v_mul_f32_e32 v106, v106, v138
	v_mul_f32_e32 v107, v107, v139
	v_mul_f32_e32 v108, v108, v140
	v_mul_f32_e32 v109, v109, v141
	v_mul_f32_e32 v110, v110, v142
	v_mul_f32_e32 v111, v111, v143
	s_or_b64 exec, exec, s[28:29]

.LBB0_1741:
	v_ashrrev_i32_e32 v0, 31, v12
	v_lshrrev_b32_e32 v0, 27, v0
	v_add_u32_e32 v0, v12, v0
	v_and_b32_e32 v1, 0x7ffffe0, v0
	v_sub_u32_e32 v1, v12, v1
	v_lshlrev_b32_e32 v0, 1, v0
	v_lshlrev_b32_e32 v19, 5, v1
	v_and_b32_e32 v8, 0xffffffc0, v0
	v_or_b32_e32 v0, v19, v5
	v_ashrrev_i32_e32 v1, 31, v0
	v_cmp_gt_i32_e32 vcc, s5, v0
	v_lshl_add_u64 v[0:1], v[0:1], 2, s[10:11]
	v_or_b32_e32 v2, v4, v8
	v_mov_b32_e32 v3, v15
	v_mov_b32_e32 v144, v2
	v_mov_b32_e32 v145, 0
	v_lshlrev_b64 v[144:145], 12, v[144:145]
	v_lshl_add_u64 v[144:145], v[0:1], 0, v[144:145]
	s_mov_b64 s[100:101], 0x2000
	v_mov_b32_e32 v80, 0
	v_mov_b32_e32 v81, 0
	v_mov_b32_e32 v82, 0
	v_mov_b32_e32 v83, 0
	v_mov_b32_e32 v84, 0
	v_mov_b32_e32 v85, 0
	v_mov_b32_e32 v86, 0
	v_mov_b32_e32 v87, 0
	v_mov_b32_e32 v88, 0
	v_mov_b32_e32 v89, 0
	v_mov_b32_e32 v90, 0
	v_mov_b32_e32 v91, 0
	v_mov_b32_e32 v92, 0
	v_mov_b32_e32 v93, 0
	v_mov_b32_e32 v94, 0
	v_mov_b32_e32 v95, 0
	v_mov_b32_e32 v96, 0
	v_mov_b32_e32 v97, 0
	v_mov_b32_e32 v98, 0
	v_mov_b32_e32 v99, 0
	v_mov_b32_e32 v100, 0
	v_mov_b32_e32 v101, 0
	v_mov_b32_e32 v102, 0
	v_mov_b32_e32 v103, 0
	v_mov_b32_e32 v104, 0
	v_mov_b32_e32 v105, 0
	v_mov_b32_e32 v106, 0
	v_mov_b32_e32 v107, 0
	v_mov_b32_e32 v108, 0
	v_mov_b32_e32 v109, 0
	v_mov_b32_e32 v110, 0
	v_mov_b32_e32 v111, 0
	s_and_saveexec_b64 s[14:15], vcc
	global_load_dword v80, v[144:145], off
	v_lshl_add_u64 v[144:145], v[144:145], 0, s[100:101]
	global_load_dword v81, v[144:145], off
	v_lshl_add_u64 v[144:145], v[144:145], 0, s[100:101]
	global_load_dword v82, v[144:145], off
	v_lshl_add_u64 v[144:145], v[144:145], 0, s[100:101]
	global_load_dword v83, v[144:145], off
	v_lshl_add_u64 v[144:145], v[144:145], 0, s[100:101]
	global_load_dword v84, v[144:145], off
	v_lshl_add_u64 v[144:145], v[144:145], 0, s[100:101]
	global_load_dword v85, v[144:145], off
	v_lshl_add_u64 v[144:145], v[144:145], 0, s[100:101]
	global_load_dword v86, v[144:145], off
	v_lshl_add_u64 v[144:145], v[144:145], 0, s[100:101]
	global_load_dword v87, v[144:145], off
	v_lshl_add_u64 v[144:145], v[144:145], 0, s[100:101]
	global_load_dword v88, v[144:145], off
	v_lshl_add_u64 v[144:145], v[144:145], 0, s[100:101]
	global_load_dword v89, v[144:145], off
	v_lshl_add_u64 v[144:145], v[144:145], 0, s[100:101]
	global_load_dword v90, v[144:145], off
	v_lshl_add_u64 v[144:145], v[144:145], 0, s[100:101]
	global_load_dword v91, v[144:145], off
	v_lshl_add_u64 v[144:145], v[144:145], 0, s[100:101]
	global_load_dword v92, v[144:145], off
	v_lshl_add_u64 v[144:145], v[144:145], 0, s[100:101]
	global_load_dword v93, v[144:145], off
	v_lshl_add_u64 v[144:145], v[144:145], 0, s[100:101]
	global_load_dword v94, v[144:145], off
	v_lshl_add_u64 v[144:145], v[144:145], 0, s[100:101]
	global_load_dword v95, v[144:145], off
	v_lshl_add_u64 v[144:145], v[144:145], 0, s[100:101]
	global_load_dword v96, v[144:145], off
	v_lshl_add_u64 v[144:145], v[144:145], 0, s[100:101]
	global_load_dword v97, v[144:145], off
	v_lshl_add_u64 v[144:145], v[144:145], 0, s[100:101]
	global_load_dword v98, v[144:145], off
	v_lshl_add_u64 v[144:145], v[144:145], 0, s[100:101]
	global_load_dword v99, v[144:145], off
	v_lshl_add_u64 v[144:145], v[144:145], 0, s[100:101]
	global_load_dword v100, v[144:145], off
	v_lshl_add_u64 v[144:145], v[144:145], 0, s[100:101]
	global_load_dword v101, v[144:145], off
	v_lshl_add_u64 v[144:145], v[144:145], 0, s[100:101]
	global_load_dword v102, v[144:145], off
	v_lshl_add_u64 v[144:145], v[144:145], 0, s[100:101]
	global_load_dword v103, v[144:145], off
	v_lshl_add_u64 v[144:145], v[144:145], 0, s[100:101]
	global_load_dword v104, v[144:145], off
	v_lshl_add_u64 v[144:145], v[144:145], 0, s[100:101]
	global_load_dword v105, v[144:145], off
	v_lshl_add_u64 v[144:145], v[144:145], 0, s[100:101]
	global_load_dword v106, v[144:145], off
	v_lshl_add_u64 v[144:145], v[144:145], 0, s[100:101]
	global_load_dword v107, v[144:145], off
	v_lshl_add_u64 v[144:145], v[144:145], 0, s[100:101]
	global_load_dword v108, v[144:145], off
	v_lshl_add_u64 v[144:145], v[144:145], 0, s[100:101]
	global_load_dword v109, v[144:145], off
	v_lshl_add_u64 v[144:145], v[144:145], 0, s[100:101]
	global_load_dword v110, v[144:145], off
	v_lshl_add_u64 v[144:145], v[144:145], 0, s[100:101]
	global_load_dword v111, v[144:145], off
	s_or_b64 exec, exec, s[14:15]
	s_waitcnt vmcnt(24)
	ds_write_b32 v3, v80 offset:0
	ds_write_b32 v3, v81 offset:264
	ds_write_b32 v3, v82 offset:528
	ds_write_b32 v3, v83 offset:792
	ds_write_b32 v3, v84 offset:1056
	ds_write_b32 v3, v85 offset:1320
	ds_write_b32 v3, v86 offset:1584
	ds_write_b32 v3, v87 offset:1848
	s_waitcnt vmcnt(16)
	ds_write_b32 v3, v88 offset:2112
	ds_write_b32 v3, v89 offset:2376
	ds_write_b32 v3, v90 offset:2640
	ds_write_b32 v3, v91 offset:2904
	ds_write_b32 v3, v92 offset:3168
	ds_write_b32 v3, v93 offset:3432
	ds_write_b32 v3, v94 offset:3696
	ds_write_b32 v3, v95 offset:3960
	s_waitcnt vmcnt(8)
	ds_write_b32 v3, v96 offset:4224
	ds_write_b32 v3, v97 offset:4488
	ds_write_b32 v3, v98 offset:4752
	ds_write_b32 v3, v99 offset:5016
	ds_write_b32 v3, v100 offset:5280
	ds_write_b32 v3, v101 offset:5544
	ds_write_b32 v3, v102 offset:5808
	ds_write_b32 v3, v103 offset:6072
	s_waitcnt vmcnt(0)
	ds_write_b32 v3, v104 offset:6336
	ds_write_b32 v3, v105 offset:6600
	ds_write_b32 v3, v106 offset:6864
	ds_write_b32 v3, v107 offset:7128
	ds_write_b32 v3, v108 offset:7392
	ds_write_b32 v3, v109 offset:7656
	ds_write_b32 v3, v110 offset:7920
	ds_write_b32 v3, v111 offset:8184

	.amdhsa_kernel _Z8mega_fwd4Args
		.amdhsa_group_segment_fixed_size 0
		.amdhsa_private_segment_fixed_size 0
		.amdhsa_kernarg_size 560
		.amdhsa_user_sgpr_count 2
		.amdhsa_user_sgpr_dispatch_ptr 0
		.amdhsa_user_sgpr_queue_ptr 0
		.amdhsa_user_sgpr_kernarg_segment_ptr 1
		.amdhsa_user_sgpr_dispatch_id 0
		.amdhsa_user_sgpr_kernarg_preload_length 0
		.amdhsa_user_sgpr_kernarg_preload_offset 0
		.amdhsa_user_sgpr_private_segment_size 0
		.amdhsa_uses_dynamic_stack 0
		.amdhsa_enable_private_segment 0
		.amdhsa_system_sgpr_workgroup_id_x 1
		.amdhsa_system_sgpr_workgroup_id_y 0
		.amdhsa_system_sgpr_workgroup_id_z 0
		.amdhsa_system_sgpr_workgroup_info 0
		.amdhsa_system_vgpr_workitem_id 2
		.amdhsa_next_free_vgpr 247
		.amdhsa_next_free_sgpr 102
		.amdhsa_accum_offset 248
		.amdhsa_reserve_vcc 1
		.amdhsa_float_round_mode_32 0
		.amdhsa_float_round_mode_16_64 0
		.amdhsa_float_denorm_mode_32 3
		.amdhsa_float_denorm_mode_16_64 3
		.amdhsa_dx10_clamp 1
		.amdhsa_ieee_mode 1
		.amdhsa_fp16_overflow 0
		.amdhsa_tg_split 0
		.amdhsa_exception_fp_ieee_invalid_op 0
		.amdhsa_exception_fp_denorm_src 0
		.amdhsa_exception_fp_ieee_div_zero 0
		.amdhsa_exception_fp_ieee_overflow 0
		.amdhsa_exception_fp_ieee_underflow 0
		.amdhsa_exception_fp_ieee_inexact 0
		.amdhsa_exception_int_div_zero 0
	.end_amdhsa_kernel

amdhsa.kernels:
  - .agpr_count:     0
    .args:
      - .offset:         0
        .size:           304
        .value_kind:     by_value
      - .offset:         304
        .size:           4
        .value_kind:     hidden_block_count_x
      - .offset:         308
        .size:           4
        .value_kind:     hidden_block_count_y
      - .offset:         312
        .size:           4
        .value_kind:     hidden_block_count_z
      - .offset:         316
        .size:           2
        .value_kind:     hidden_group_size_x
      - .offset:         318
        .size:           2
        .value_kind:     hidden_group_size_y
      - .offset:         320
        .size:           2
        .value_kind:     hidden_group_size_z
      - .offset:         322
        .size:           2
        .value_kind:     hidden_remainder_x
      - .offset:         324
        .size:           2
        .value_kind:     hidden_remainder_y
      - .offset:         326
        .size:           2
        .value_kind:     hidden_remainder_z
      - .offset:         344
        .size:           8
        .value_kind:     hidden_global_offset_x
      - .offset:         352
        .size:           8
        .value_kind:     hidden_global_offset_y
      - .offset:         360
        .size:           8
        .value_kind:     hidden_global_offset_z
      - .offset:         368
        .size:           2
        .value_kind:     hidden_grid_dims
      - .offset:         392
        .size:           8
        .value_kind:     hidden_multigrid_sync_arg
      - .offset:         424
        .size:           4
        .value_kind:     hidden_dynamic_lds_size
    .group_segment_fixed_size: 0
    .kernarg_segment_align: 8
    .kernarg_segment_size: 560
    .language:       OpenCL C
    .language_version:
      - 2
      - 0
    .max_flat_workgroup_size: 512
    .name:           _Z8mega_fwd4Args
    .private_segment_fixed_size: 0
    .sgpr_count:     108
    .sgpr_spill_count: 6
    .symbol:         _Z8mega_fwd4Args.kd
    .uniform_work_group_size: 1
    .uses_dynamic_stack: false
    .vgpr_count:     247
    .vgpr_spill_count: 0
    .wavefront_size: 64
